# v10 + row-group pipelining: LayerNorm phases remapped to the GEMM row groups; seams P6|P7|P8|P9|P10, P18|P19|P20, P21|P22 use 32-workgroup group barriers instead of grid barriers
# baseline (speedup 1.0000x reference)
.LBB0_735:
	s_cmp_gt_i32 s73, 7
	s_cselect_b64 s[6:7], -1, 0
	s_and_b64 s[2:3], s[4:5], s[6:7]
	s_andn2_b64 vcc, exec, s[2:3]
	s_cbranch_vccnz .LBB0_789
	s_cmpk_lg_i32 s80, 0x100
	s_cbranch_scc1 .Lgb_orig_0
	s_waitcnt vmcnt(0)
	s_barrier
	s_and_saveexec_b64 s[4:5], s[86:87]
	s_cbranch_execz .Lgb_done_0
	buffer_wbl2 sc1
	s_waitcnt vmcnt(0)
	s_and_b32 s2, s76, 7
	s_lshl_b32 s2, s2, 8
	s_add_u32 s2, s74, s2
	s_addc_u32 s3, s75, 0
	v_mov_b32_e32 v2, 0x4000
	v_mov_b32_e32 v3, 1
	v_mov_b32_e32 v5, 0
	global_atomic_add v2, v3, s[2:3]
.Lgb_spin_0:
	global_load_dword v4, v2, s[2:3] sc1
	v_add_u32_e32 v5, 1, v5
	s_waitcnt vmcnt(0)
	v_cmp_gt_u32_e32 vcc, 32, v4
	s_cbranch_vccz .Lgb_out_0
	s_sleep 1
	v_cmp_gt_u32_e32 vcc, 0x8000, v5
	s_cbranch_vccnz .Lgb_spin_0

.LBB0_789:
	s_cmp_lt_i32 s72, 8
	s_cselect_b64 s[2:3], -1, 0
	s_and_b64 s[4:5], s[2:3], s[6:7]
	s_andn2_b64 vcc, exec, s[4:5]
	s_cbranch_vccnz .LBB0_796
	s_load_dwordx2 s[98:99], s[0:1], 0xb0
	s_load_dwordx2 s[100:101], s[0:1], 0xb8
	v_lshlrev_b32_e32 v2, 4, v0
	v_add_u32_e32 v3, 0x2000, v2
	v_and_b32_e32 v251, 63, v0
	v_lshlrev_b32_e32 v251, 5, v251
	s_waitcnt lgkmcnt(0)
	global_load_dwordx4 v[4:7], v2, s[98:99]
	global_load_dwordx4 v[8:11], v3, s[98:99]
	global_load_dwordx4 v[12:15], v2, s[100:101]
	global_load_dwordx4 v[16:19], v3, s[100:101]
	s_waitcnt vmcnt(0)
	ds_write_b128 v2, v[4:7]
	ds_write_b128 v3, v[8:11]
	ds_write_b128 v2, v[12:15] offset:16384
	ds_write_b128 v3, v[16:19] offset:16384
	s_waitcnt lgkmcnt(0)
	s_barrier
	s_waitcnt vmcnt(0)
	s_and_b32 s99, s76, 7
	s_lshl_b32 s99, s99, 8
	s_lshr_b32 s100, s76, 3
	s_or_b32 s99, s99, s100
	s_and_b32 s100, s76, 7
	s_add_i32 s100, s100, 1
	s_lshl_b32 s100, s100, 11
	s_cmpk_lg_i32 s80, 0x100
	s_cselect_b32 s99, s76, s99
	s_cselect_b32 s2, 0x4000, s100
	v_lshl_or_b32 v66, s99, 3, v1
	v_cmp_gt_i32_e32 vcc, s2, v66
	s_and_saveexec_b64 s[12:13], vcc
	s_cbranch_execz .LBB0_795
	v_ashrrev_i32_e32 v67, 31, v66
	v_and_b32_e32 v38, 63, v0
	v_lshlrev_b64 v[68:69], 13, v[66:67]
	v_mov_b32_e32 v70, 0
	v_lshl_add_u64 v[2:3], s[90:91], 0, v[68:69]
	v_lshlrev_b32_e32 v34, 4, v38
	v_mov_b32_e32 v35, v70
	v_lshl_add_u64 v[18:19], v[2:3], 0, v[34:35]
	s_movk_i32 s3, 0x1000
	v_add_co_u32_e32 v36, vcc, s3, v18
	global_load_dwordx4 v[2:5], v[18:19], off
	global_load_dwordx4 v[6:9], v[18:19], off offset:1024
	global_load_dwordx4 v[10:13], v[18:19], off offset:2048
	global_load_dwordx4 v[14:17], v[18:19], off offset:3072
	v_addc_co_u32_e32 v37, vcc, 0, v19, vcc
	global_load_dwordx4 v[18:21], v[36:37], off
	global_load_dwordx4 v[22:25], v[36:37], off offset:1024
	global_load_dwordx4 v[26:29], v[36:37], off offset:2048
	global_load_dwordx4 v[30:33], v[36:37], off offset:3072
	v_lshl_add_u64 v[72:73], s[90:91], 0, v[34:35]
	v_mbcnt_lo_u32_b32 v35, -1, 0
	v_mbcnt_hi_u32_b32 v35, -1, v35
	v_and_b32_e32 v36, 64, v35
	v_add_u32_e32 v36, 64, v36
	v_xor_b32_e32 v37, 32, v35
	v_cmp_lt_i32_e32 vcc, v37, v36
	s_load_dwordx4 s[8:11], s[0:1], 0xb0
	v_mov_b32_e32 v39, v70
	v_cndmask_b32_e32 v37, v35, v37, vcc
	v_lshlrev_b32_e32 v104, 2, v37
	v_xor_b32_e32 v37, 16, v35
	v_cmp_lt_i32_e32 vcc, v37, v36
	s_lshl_b32 s14, s80, 3
	s_cmpk_lg_i32 s80, 0x100
	s_cselect_b32 s14, s14, 0x100
	s_ashr_i32 s15, s14, 31
	v_cndmask_b32_e32 v37, v35, v37, vcc
	v_lshlrev_b32_e32 v105, 2, v37
	v_xor_b32_e32 v37, 8, v35
	v_cmp_lt_i32_e32 vcc, v37, v36
	v_or_b32_e32 v68, v68, v34
	s_lshl_b64 s[16:17], s[14:15], 13
	v_cndmask_b32_e32 v37, v35, v37, vcc
	v_lshlrev_b32_e32 v106, 2, v37
	v_xor_b32_e32 v37, 4, v35
	v_cmp_lt_i32_e32 vcc, v37, v36
	s_mov_b64 s[18:19], 0
	s_mov_b32 s20, 0xb9800000
	v_cndmask_b32_e32 v37, v35, v37, vcc
	v_lshlrev_b32_e32 v107, 2, v37
	v_xor_b32_e32 v37, 2, v35
	v_cmp_lt_i32_e32 vcc, v37, v36
	s_mov_b32 s21, 0x800000
	s_mov_b32 s22, 0xb510000
	v_cndmask_b32_e32 v37, v35, v37, vcc
	v_lshlrev_b32_e32 v108, 2, v37
	v_xor_b32_e32 v37, 1, v35
	v_cmp_lt_i32_e32 vcc, v37, v36
	v_lshlrev_b32_e32 v36, 5, v38
	s_mov_b32 s23, 0xb511000
	v_cndmask_b32_e32 v35, v35, v37, vcc
	v_cmp_eq_u32_e32 vcc, 0, v38
	v_or_b32_e32 v38, 0x1000, v36
	s_waitcnt lgkmcnt(0)
	v_lshl_add_u64 v[78:79], s[8:9], 0, v[38:39]
	v_lshl_add_u64 v[80:81], s[10:11], 0, v[38:39]
	v_or_b32_e32 v38, 0x1800, v36
	v_mov_b32_e32 v37, v70
	v_lshl_add_u64 v[82:83], s[8:9], 0, v[38:39]
	v_lshl_add_u64 v[84:85], s[10:11], 0, v[38:39]
	v_or_b32_e32 v38, 0x2000, v36
	v_lshlrev_b32_e32 v109, 2, v35
	v_lshl_add_u64 v[74:75], s[8:9], 0, v[36:37]
	v_lshl_add_u64 v[76:77], s[10:11], 0, v[36:37]
	v_lshl_add_u64 v[86:87], s[8:9], 0, v[38:39]
	v_lshl_add_u64 v[88:89], s[10:11], 0, v[38:39]
	v_or_b32_e32 v38, 0x2800, v36
	v_or_b32_e32 v36, 0x3000, v36
	v_mov_b32_e32 v35, 0x3800
	v_lshl_add_u64 v[94:95], s[8:9], 0, v[36:37]
	v_lshl_add_u64 v[96:97], s[10:11], 0, v[36:37]
	v_lshl_or_b32 v36, v0, 5, v35
	v_lshl_add_u64 v[98:99], s[8:9], 0, v[36:37]
	v_lshl_add_u64 v[100:101], s[10:11], 0, v[36:37]
	v_mov_b64_e32 v[36:37], 0x65c10000
	v_lshl_add_u64 v[90:91], s[8:9], 0, v[38:39]
	v_lshl_add_u64 v[92:93], s[10:11], 0, v[38:39]
	v_lshl_add_u64 v[102:103], v[66:67], 3, v[36:37]
	s_lshl_b64 s[10:11], s[14:15], 3
	s_add_i32 s15, s2, -1
	v_mov_b32_e32 v67, 0x3727c5ac
	s_branch .LBB0_793

.LBB0_796:
	s_cmp_gt_i32 s73, 8
	s_cselect_b64 s[6:7], -1, 0
	s_and_b64 s[2:3], s[4:5], s[6:7]
	s_andn2_b64 vcc, exec, s[2:3]
	s_cbranch_vccnz .LBB0_850
	s_cmpk_lg_i32 s80, 0x100
	s_cbranch_scc1 .Lgb_orig_1
	s_waitcnt vmcnt(0)
	s_barrier
	s_and_saveexec_b64 s[4:5], s[86:87]
	s_cbranch_execz .Lgb_done_1
	buffer_wbl2 sc1
	s_waitcnt vmcnt(0)
	s_and_b32 s2, s76, 7
	s_lshl_b32 s2, s2, 8
	s_add_u32 s2, s74, s2
	s_addc_u32 s3, s75, 0
	v_mov_b32_e32 v2, 0x4800
	v_mov_b32_e32 v3, 1
	v_mov_b32_e32 v5, 0
	global_atomic_add v2, v3, s[2:3]

.LBB0_879:
	s_waitcnt vmcnt(0)
	s_cmp_gt_i32 s73, 9
	s_cselect_b64 s[6:7], -1, 0
	s_and_b64 s[2:3], s[4:5], s[6:7]
	s_andn2_b64 vcc, exec, s[2:3]
	s_cbranch_vccnz .LBB0_933
	s_cmpk_lg_i32 s80, 0x100
	s_cbranch_scc1 .Lgb_orig_2
	s_waitcnt vmcnt(0)
	s_barrier
	s_and_saveexec_b64 s[4:5], s[86:87]
	s_cbranch_execz .Lgb_done_2
	buffer_wbl2 sc1
	s_waitcnt vmcnt(0)
	s_and_b32 s2, s76, 7
	s_lshl_b32 s2, s2, 8
	s_add_u32 s2, s74, s2
	s_addc_u32 s3, s75, 0
	v_mov_b32_e32 v2, 0x5000
	v_mov_b32_e32 v3, 1
	v_mov_b32_e32 v5, 0
	global_atomic_add v2, v3, s[2:3]

.LBB0_962:
	s_load_dwordx2 s[2:3], s[0:1], 0x310
	s_waitcnt lgkmcnt(0)
	s_cmp_gt_i32 s3, 10
	s_cselect_b64 s[6:7], -1, 0
	s_and_b64 s[2:3], s[4:5], s[6:7]
	s_andn2_b64 vcc, exec, s[2:3]
	s_cbranch_vccnz .LBB0_1016
	s_cmpk_lg_i32 s80, 0x100
	s_cbranch_scc1 .Lgb_orig_3
	s_waitcnt vmcnt(0)
	s_barrier
	s_and_saveexec_b64 s[4:5], s[86:87]
	s_cbranch_execz .Lgb_done_3
	buffer_wbl2 sc1
	s_waitcnt vmcnt(0)
	s_and_b32 s2, s76, 7
	s_lshl_b32 s2, s2, 8
	s_add_u32 s2, s74, s2
	s_addc_u32 s3, s75, 0
	v_mov_b32_e32 v2, 0x5800
	v_mov_b32_e32 v3, 1
	v_mov_b32_e32 v5, 0
	global_atomic_add v2, v3, s[2:3]

.LBB0_1016:
	s_load_dwordx2 s[2:3], s[0:1], 0x310
	s_waitcnt lgkmcnt(0)
	s_cmp_lt_i32 s2, 11
	s_cselect_b64 s[2:3], -1, 0
	s_and_b64 s[4:5], s[2:3], s[6:7]
	s_andn2_b64 vcc, exec, s[4:5]
	s_cbranch_vccnz .LBB0_1023
	s_load_dwordx2 s[98:99], s[0:1], 0xc0
	s_load_dwordx2 s[100:101], s[0:1], 0xc8
	v_lshlrev_b32_e32 v2, 4, v0
	v_add_u32_e32 v3, 0x2000, v2
	v_and_b32_e32 v251, 63, v0
	v_lshlrev_b32_e32 v251, 5, v251
	s_waitcnt lgkmcnt(0)
	global_load_dwordx4 v[4:7], v2, s[98:99]
	global_load_dwordx4 v[8:11], v3, s[98:99]
	global_load_dwordx4 v[12:15], v2, s[100:101]
	global_load_dwordx4 v[16:19], v3, s[100:101]
	s_waitcnt vmcnt(0)
	ds_write_b128 v2, v[4:7]
	ds_write_b128 v3, v[8:11]
	ds_write_b128 v2, v[12:15] offset:16384
	ds_write_b128 v3, v[16:19] offset:16384
	s_waitcnt lgkmcnt(0)
	s_barrier
	s_waitcnt vmcnt(0)
	s_and_b32 s99, s76, 7
	s_lshl_b32 s99, s99, 8
	s_lshr_b32 s100, s76, 3
	s_or_b32 s99, s99, s100
	s_and_b32 s100, s76, 7
	s_add_i32 s100, s100, 1
	s_lshl_b32 s100, s100, 11
	s_cmpk_lg_i32 s80, 0x100
	s_cselect_b32 s99, s76, s99
	s_cselect_b32 s2, 0x4000, s100
	v_lshl_or_b32 v66, s99, 3, v1
	v_cmp_gt_i32_e32 vcc, s2, v66
	s_and_saveexec_b64 s[12:13], vcc
	s_cbranch_execz .LBB0_1022
	v_ashrrev_i32_e32 v67, 31, v66
	v_and_b32_e32 v38, 63, v0
	v_lshlrev_b64 v[68:69], 13, v[66:67]
	v_mov_b32_e32 v70, 0
	v_lshl_add_u64 v[2:3], s[94:95], 0, v[68:69]
	v_lshlrev_b32_e32 v34, 4, v38
	v_mov_b32_e32 v35, v70
	v_lshl_add_u64 v[18:19], v[2:3], 0, v[34:35]
	s_movk_i32 s3, 0x1000
	v_add_co_u32_e32 v36, vcc, s3, v18
	global_load_dwordx4 v[2:5], v[18:19], off
	global_load_dwordx4 v[6:9], v[18:19], off offset:1024
	global_load_dwordx4 v[10:13], v[18:19], off offset:2048
	global_load_dwordx4 v[14:17], v[18:19], off offset:3072
	v_addc_co_u32_e32 v37, vcc, 0, v19, vcc
	global_load_dwordx4 v[18:21], v[36:37], off
	global_load_dwordx4 v[22:25], v[36:37], off offset:1024
	global_load_dwordx4 v[26:29], v[36:37], off offset:2048
	global_load_dwordx4 v[30:33], v[36:37], off offset:3072
	v_lshl_add_u64 v[72:73], s[94:95], 0, v[34:35]
	v_mbcnt_lo_u32_b32 v35, -1, 0
	v_mbcnt_hi_u32_b32 v35, -1, v35
	v_and_b32_e32 v36, 64, v35
	v_add_u32_e32 v36, 64, v36
	v_xor_b32_e32 v37, 32, v35
	v_cmp_lt_i32_e32 vcc, v37, v36
	s_load_dwordx4 s[8:11], s[0:1], 0xc0
	v_mov_b32_e32 v39, v70
	v_cndmask_b32_e32 v37, v35, v37, vcc
	v_lshlrev_b32_e32 v104, 2, v37
	v_xor_b32_e32 v37, 16, v35
	v_cmp_lt_i32_e32 vcc, v37, v36
	s_lshl_b32 s14, s80, 3
	s_cmpk_lg_i32 s80, 0x100
	s_cselect_b32 s14, s14, 0x100
	s_ashr_i32 s15, s14, 31
	v_cndmask_b32_e32 v37, v35, v37, vcc
	v_lshlrev_b32_e32 v105, 2, v37
	v_xor_b32_e32 v37, 8, v35
	v_cmp_lt_i32_e32 vcc, v37, v36
	v_or_b32_e32 v68, v68, v34
	s_lshl_b64 s[16:17], s[14:15], 13
	v_cndmask_b32_e32 v37, v35, v37, vcc
	v_lshlrev_b32_e32 v106, 2, v37
	v_xor_b32_e32 v37, 4, v35
	v_cmp_lt_i32_e32 vcc, v37, v36
	s_mov_b64 s[18:19], 0
	s_mov_b32 s20, 0xb9800000
	v_cndmask_b32_e32 v37, v35, v37, vcc
	v_lshlrev_b32_e32 v107, 2, v37
	v_xor_b32_e32 v37, 2, v35
	v_cmp_lt_i32_e32 vcc, v37, v36
	s_mov_b32 s21, 0x800000
	s_mov_b32 s22, 0xb510000
	v_cndmask_b32_e32 v37, v35, v37, vcc
	v_lshlrev_b32_e32 v108, 2, v37
	v_xor_b32_e32 v37, 1, v35
	v_cmp_lt_i32_e32 vcc, v37, v36
	v_lshlrev_b32_e32 v36, 5, v38
	s_mov_b32 s23, 0xb511000
	v_cndmask_b32_e32 v35, v35, v37, vcc
	v_cmp_eq_u32_e32 vcc, 0, v38
	v_or_b32_e32 v38, 0x1000, v36
	s_waitcnt lgkmcnt(0)
	v_lshl_add_u64 v[78:79], s[8:9], 0, v[38:39]
	v_lshl_add_u64 v[80:81], s[10:11], 0, v[38:39]
	v_or_b32_e32 v38, 0x1800, v36
	v_mov_b32_e32 v37, v70
	v_lshl_add_u64 v[82:83], s[8:9], 0, v[38:39]
	v_lshl_add_u64 v[84:85], s[10:11], 0, v[38:39]
	v_or_b32_e32 v38, 0x2000, v36
	v_lshlrev_b32_e32 v109, 2, v35
	v_lshl_add_u64 v[74:75], s[8:9], 0, v[36:37]
	v_lshl_add_u64 v[76:77], s[10:11], 0, v[36:37]
	v_lshl_add_u64 v[86:87], s[8:9], 0, v[38:39]
	v_lshl_add_u64 v[88:89], s[10:11], 0, v[38:39]
	v_or_b32_e32 v38, 0x2800, v36
	v_or_b32_e32 v36, 0x3000, v36
	v_mov_b32_e32 v35, 0x3800
	v_lshl_add_u64 v[94:95], s[8:9], 0, v[36:37]
	v_lshl_add_u64 v[96:97], s[10:11], 0, v[36:37]
	v_lshl_or_b32 v36, v0, 5, v35
	v_lshl_add_u64 v[98:99], s[8:9], 0, v[36:37]
	v_lshl_add_u64 v[100:101], s[10:11], 0, v[36:37]
	v_mov_b64_e32 v[36:37], 0x65c10000
	v_lshl_add_u64 v[90:91], s[8:9], 0, v[38:39]
	v_lshl_add_u64 v[92:93], s[10:11], 0, v[38:39]
	v_lshl_add_u64 v[102:103], v[66:67], 3, v[36:37]
	s_lshl_b64 s[10:11], s[14:15], 3
	s_add_i32 s15, s2, -1
	v_mov_b32_e32 v67, 0x3727c5ac
	s_branch .LBB0_1020

.LBB0_2149:
	s_load_dwordx2 s[56:57], s[0:1], 0x310
	v_readlane_b32 s58, v250, 4
	v_readlane_b32 s59, v250, 5
	s_waitcnt lgkmcnt(0)
	s_cmp_gt_i32 s57, 19
	s_cselect_b64 s[6:7], -1, 0
	s_and_b64 s[2:3], s[4:5], s[6:7]
	s_andn2_b64 vcc, exec, s[2:3]
	s_cbranch_vccnz .LBB0_2203
	s_cmpk_lg_i32 s80, 0x100
	s_cbranch_scc1 .Lgb_orig_4
	s_waitcnt vmcnt(0)
	s_barrier
	s_and_saveexec_b64 s[4:5], s[86:87]
	s_cbranch_execz .Lgb_done_4
	buffer_wbl2 sc1
	s_waitcnt vmcnt(0)
	s_and_b32 s2, s76, 7
	s_lshl_b32 s2, s2, 8
	s_add_u32 s2, s74, s2
	s_addc_u32 s3, s75, 0
	v_mov_b32_e32 v2, 0x6000
	v_mov_b32_e32 v3, 1
	v_mov_b32_e32 v5, 0
	global_atomic_add v2, v3, s[2:3]

.LBB0_2203:
	s_cmp_lt_i32 s56, 20
	s_cselect_b64 s[2:3], -1, 0
	s_and_b64 s[4:5], s[2:3], s[6:7]
	s_andn2_b64 vcc, exec, s[4:5]
	s_cbranch_vccnz .LBB0_2210
	s_load_dwordx2 s[98:99], s[0:1], 0xb0
	s_load_dwordx2 s[100:101], s[0:1], 0xb8
	v_lshlrev_b32_e32 v2, 4, v0
	v_add_u32_e32 v3, 0x2000, v2
	v_and_b32_e32 v251, 63, v0
	v_lshlrev_b32_e32 v251, 5, v251
	s_waitcnt lgkmcnt(0)
	s_add_u32 s98, s98, 0x4000
	s_addc_u32 s99, s99, 0
	s_add_u32 s100, s100, 0x4000
	s_addc_u32 s101, s101, 0
	global_load_dwordx4 v[4:7], v2, s[98:99]
	global_load_dwordx4 v[8:11], v3, s[98:99]
	global_load_dwordx4 v[12:15], v2, s[100:101]
	global_load_dwordx4 v[16:19], v3, s[100:101]
	s_waitcnt vmcnt(0)
	ds_write_b128 v2, v[4:7]
	ds_write_b128 v3, v[8:11]
	ds_write_b128 v2, v[12:15] offset:16384
	ds_write_b128 v3, v[16:19] offset:16384
	s_waitcnt lgkmcnt(0)
	s_barrier
	s_waitcnt vmcnt(0)
	s_and_b32 s99, s76, 7
	s_lshl_b32 s99, s99, 8
	s_lshr_b32 s100, s76, 3
	s_or_b32 s99, s99, s100
	s_and_b32 s100, s76, 7
	s_add_i32 s100, s100, 1
	s_lshl_b32 s100, s100, 11
	s_cmpk_lg_i32 s80, 0x100
	s_cselect_b32 s99, s76, s99
	s_cselect_b32 s2, 0x4000, s100
	v_lshl_or_b32 v66, s99, 3, v1
	v_cmp_gt_i32_e32 vcc, s2, v66
	s_and_saveexec_b64 s[10:11], vcc
	s_cbranch_execz .LBB0_2209
	v_ashrrev_i32_e32 v67, 31, v66
	v_and_b32_e32 v38, 63, v0
	v_lshlrev_b64 v[68:69], 13, v[66:67]
	v_mov_b32_e32 v70, 0
	v_lshl_add_u64 v[2:3], s[90:91], 0, v[68:69]
	v_lshlrev_b32_e32 v34, 4, v38
	v_mov_b32_e32 v35, v70
	v_lshl_add_u64 v[18:19], v[2:3], 0, v[34:35]
	s_movk_i32 s3, 0x1000
	v_add_co_u32_e32 v36, vcc, s3, v18
	global_load_dwordx4 v[2:5], v[18:19], off
	global_load_dwordx4 v[6:9], v[18:19], off offset:1024
	global_load_dwordx4 v[10:13], v[18:19], off offset:2048
	global_load_dwordx4 v[14:17], v[18:19], off offset:3072
	v_addc_co_u32_e32 v37, vcc, 0, v19, vcc
	global_load_dwordx4 v[18:21], v[36:37], off
	global_load_dwordx4 v[22:25], v[36:37], off offset:1024
	global_load_dwordx4 v[26:29], v[36:37], off offset:2048
	global_load_dwordx4 v[30:33], v[36:37], off offset:3072
	v_lshl_add_u64 v[72:73], s[90:91], 0, v[34:35]
	v_mbcnt_lo_u32_b32 v35, -1, 0
	v_mbcnt_hi_u32_b32 v35, -1, v35
	v_and_b32_e32 v36, 64, v35
	v_add_u32_e32 v36, 64, v36
	v_xor_b32_e32 v37, 32, v35
	v_cmp_lt_i32_e32 vcc, v37, v36
	s_load_dwordx4 s[16:19], s[0:1], 0xb0
	s_lshl_b32 s12, s80, 3
	s_cmpk_lg_i32 s80, 0x100
	s_cselect_b32 s12, s12, 0x100
	v_cndmask_b32_e32 v37, v35, v37, vcc
	v_lshlrev_b32_e32 v108, 2, v37
	v_xor_b32_e32 v37, 16, v35
	v_cmp_lt_i32_e32 vcc, v37, v36
	s_waitcnt lgkmcnt(0)
	s_add_u32 s6, s18, 0x4000
	s_addc_u32 s7, s19, 0
	v_cndmask_b32_e32 v37, v35, v37, vcc
	v_lshlrev_b32_e32 v109, 2, v37
	v_xor_b32_e32 v37, 8, v35
	v_cmp_lt_i32_e32 vcc, v37, v36
	s_add_u32 s8, s16, 0x4000
	s_addc_u32 s9, s17, 0
	v_cndmask_b32_e32 v37, v35, v37, vcc
	v_lshlrev_b32_e32 v110, 2, v37
	v_xor_b32_e32 v37, 4, v35
	v_cmp_lt_i32_e32 vcc, v37, v36
	v_mov_b32_e32 v39, v70
	s_ashr_i32 s13, s12, 31
	v_cndmask_b32_e32 v37, v35, v37, vcc
	v_lshlrev_b32_e32 v111, 2, v37
	v_xor_b32_e32 v37, 2, v35
	v_cmp_lt_i32_e32 vcc, v37, v36
	s_lshl_b64 s[14:15], s[12:13], 3
	v_or_b32_e32 v68, v68, v34
	v_cndmask_b32_e32 v37, v35, v37, vcc
	v_lshlrev_b32_e32 v112, 2, v37
	v_xor_b32_e32 v37, 1, v35
	v_cmp_lt_i32_e32 vcc, v37, v36
	v_lshlrev_b32_e32 v36, 5, v38
	s_lshl_b64 s[16:17], s[12:13], 13
	v_cndmask_b32_e32 v35, v35, v37, vcc
	v_cmp_eq_u32_e32 vcc, 0, v38
	v_or_b32_e32 v38, 0x800, v36
	v_lshl_add_u64 v[78:79], s[8:9], 0, v[38:39]
	v_lshl_add_u64 v[80:81], s[6:7], 0, v[38:39]
	v_or_b32_e32 v38, 0x1000, v36
	v_lshl_add_u64 v[82:83], s[8:9], 0, v[38:39]
	v_lshl_add_u64 v[84:85], s[6:7], 0, v[38:39]
	v_or_b32_e32 v38, 0x1800, v36
	v_mov_b32_e32 v37, v70
	v_lshl_add_u64 v[86:87], s[8:9], 0, v[38:39]
	v_lshl_add_u64 v[88:89], s[6:7], 0, v[38:39]
	v_or_b32_e32 v38, 0x2000, v36
	v_lshlrev_b32_e32 v113, 2, v35
	v_lshl_add_u64 v[74:75], s[8:9], 0, v[36:37]
	v_lshl_add_u64 v[76:77], s[6:7], 0, v[36:37]
	v_lshl_add_u64 v[90:91], s[8:9], 0, v[38:39]
	v_lshl_add_u64 v[92:93], s[6:7], 0, v[38:39]
	v_or_b32_e32 v38, 0x2800, v36
	v_or_b32_e32 v36, 0x3000, v36
	v_mov_b32_e32 v35, 0x3800
	v_lshl_add_u64 v[98:99], s[8:9], 0, v[36:37]
	v_lshl_add_u64 v[100:101], s[6:7], 0, v[36:37]
	v_lshl_or_b32 v36, v0, 5, v35
	v_lshl_add_u64 v[102:103], s[8:9], 0, v[36:37]
	v_lshl_add_u64 v[104:105], s[6:7], 0, v[36:37]
	v_mov_b64_e32 v[36:37], 0x65c10000
	v_lshl_add_u64 v[94:95], s[8:9], 0, v[38:39]
	v_lshl_add_u64 v[96:97], s[6:7], 0, v[38:39]
	v_lshl_add_u64 v[106:107], v[66:67], 3, v[36:37]
	s_mov_b64 s[18:19], 0
	s_add_i32 s13, s2, -1
	s_mov_b32 s20, 0xb9800000
	v_mov_b32_e32 v67, 0x3727c5ac
	s_mov_b32 s21, 0x800000
	s_mov_b32 s22, 0xb510000
	s_mov_b32 s23, 0xb511000
	s_branch .LBB0_2207

.LBB0_2210:
	s_cmp_gt_i32 s57, 20
	s_cselect_b64 s[6:7], -1, 0
	s_and_b64 s[2:3], s[4:5], s[6:7]
	s_andn2_b64 vcc, exec, s[2:3]
	s_cbranch_vccnz .LBB0_2264
	s_cmpk_lg_i32 s80, 0x100
	s_cbranch_scc1 .Lgb_orig_5
	s_waitcnt vmcnt(0)
	s_barrier
	s_and_saveexec_b64 s[4:5], s[86:87]
	s_cbranch_execz .Lgb_done_5
	buffer_wbl2 sc1
	s_waitcnt vmcnt(0)
	s_and_b32 s2, s76, 7
	s_lshl_b32 s2, s2, 8
	s_add_u32 s2, s74, s2
	s_addc_u32 s3, s75, 0
	v_mov_b32_e32 v2, 0x6800
	v_mov_b32_e32 v3, 1
	v_mov_b32_e32 v5, 0
	global_atomic_add v2, v3, s[2:3]

.LBB0_2376:
	s_cmp_gt_i32 s57, 22
	s_cselect_b64 s[6:7], -1, 0
	s_and_b64 s[2:3], s[12:13], s[6:7]
	s_andn2_b64 vcc, exec, s[2:3]
	s_cbranch_vccnz .LBB0_2430
	s_cmpk_lg_i32 s80, 0x100
	s_cbranch_scc1 .Lgb_orig_6
	s_waitcnt vmcnt(0)
	s_barrier
	s_and_saveexec_b64 s[8:9], s[86:87]
	s_cbranch_execz .Lgb_done_6
	buffer_wbl2 sc1
	s_waitcnt vmcnt(0)
	s_and_b32 s2, s76, 7
	s_lshl_b32 s2, s2, 8
	s_add_u32 s2, s74, s2
	s_addc_u32 s3, s75, 0
	v_mov_b32_e32 v2, 0x7000
	v_mov_b32_e32 v3, 1
	v_mov_b32_e32 v5, 0
	global_atomic_add v2, v3, s[2:3]

.Lgb_done_6:
	s_or_b64 exec, exec, s[8:9]
	s_barrier
	s_branch .LBB0_2430
.Lgb_orig_6:
	s_waitcnt vmcnt(0)
	s_waitcnt vmcnt(0)
	s_barrier
	s_and_saveexec_b64 s[8:9], s[86:87]
	s_cbranch_execz .LBB0_2429
	s_add_i32 s2, 0, 0x25f00
	v_mov_b32_e32 v2, s2
	s_waitcnt vmcnt(0) expcnt(0) lgkmcnt(0)
	ds_read_b32 v4, v2
	s_add_i32 s2, 0, 0x25f04
	v_mov_b32_e32 v2, s2
	ds_read_b32 v2, v2
	s_waitcnt lgkmcnt(1)
	v_cmp_ne_u32_e32 vcc, 0, v4
	s_cbranch_vccnz .LBB0_2393
	v_readlane_b32 s10, v250, 0
	v_readlane_b32 s11, v250, 1
	s_load_dwordx2 s[2:3], s[10:11], 0x4
	s_add_u32 s10, s74, 0x1000
	s_addc_u32 s11, s75, 0
	s_add_u32 s12, s74, 0x1100
	s_addc_u32 s13, s75, 0
	s_add_u32 s14, s74, 0x1200
	s_addc_u32 s15, s75, 0
	s_waitcnt lgkmcnt(0)
	s_mul_i32 s2, s2, s80
	s_add_u32 s16, s74, 0x1300
	s_mul_i32 s2, s2, s3
	s_addc_u32 s17, s75, 0
	s_mov_b32 s3, 1
	v_mov_b32_e32 v18, 0
	s_branch .LBB0_2381

.LBB0_2430:
	s_cmp_lt_i32 s56, 23
	s_cselect_b64 s[2:3], -1, 0
	s_and_b64 s[6:7], s[2:3], s[6:7]
	s_andn2_b64 vcc, exec, s[6:7]
	s_cbranch_vccnz .LBB0_2437
	s_load_dwordx2 s[98:99], s[0:1], 0xc0
	s_load_dwordx2 s[100:101], s[0:1], 0xc8
	v_lshlrev_b32_e32 v2, 4, v0
	v_add_u32_e32 v3, 0x2000, v2
	v_and_b32_e32 v251, 63, v0
	v_lshlrev_b32_e32 v251, 5, v251
	s_waitcnt lgkmcnt(0)
	s_add_u32 s98, s98, 0x4000
	s_addc_u32 s99, s99, 0
	s_add_u32 s100, s100, 0x4000
	s_addc_u32 s101, s101, 0
	global_load_dwordx4 v[4:7], v2, s[98:99]
	global_load_dwordx4 v[8:11], v3, s[98:99]
	global_load_dwordx4 v[12:15], v2, s[100:101]
	global_load_dwordx4 v[16:19], v3, s[100:101]
	s_waitcnt vmcnt(0)
	ds_write_b128 v2, v[4:7]
	ds_write_b128 v3, v[8:11]
	ds_write_b128 v2, v[12:15] offset:16384
	ds_write_b128 v3, v[16:19] offset:16384
	s_waitcnt lgkmcnt(0)
	s_barrier
	s_and_b32 s99, s76, 7
	s_lshl_b32 s99, s99, 8
	s_lshr_b32 s100, s76, 3
	s_or_b32 s99, s99, s100
	s_and_b32 s100, s76, 7
	s_add_i32 s100, s100, 1
	s_lshl_b32 s100, s100, 11
	s_cmpk_lg_i32 s80, 0x100
	s_cselect_b32 s99, s76, s99
	s_cselect_b32 s14, 0x4000, s100
	v_lshl_or_b32 v34, s99, 3, v1
	v_cmp_gt_i32_e32 vcc, s14, v34
	s_and_saveexec_b64 s[2:3], vcc
	s_cbranch_execz .LBB0_2436
	v_ashrrev_i32_e32 v35, 31, v34
	v_lshlrev_b32_e32 v1, 3, v0
	v_lshlrev_b64 v[2:3], 13, v[34:35]
	v_and_b32_e32 v1, 0x1f8, v1
	v_mov_b32_e32 v36, 0
	v_lshl_add_u64 v[2:3], s[4:5], 0, v[2:3]
	v_lshlrev_b32_e32 v38, 1, v1
	v_mov_b32_e32 v39, v36
	v_lshl_add_u64 v[18:19], v[2:3], 0, v[38:39]
	s_movk_i32 s15, 0x1000
	v_add_co_u32_e32 v40, vcc, s15, v18
	global_load_dwordx4 v[2:5], v[18:19], off
	global_load_dwordx4 v[6:9], v[18:19], off offset:1024
	global_load_dwordx4 v[10:13], v[18:19], off offset:2048
	global_load_dwordx4 v[14:17], v[18:19], off offset:3072
	v_addc_co_u32_e32 v41, vcc, 0, v19, vcc
	global_load_dwordx4 v[18:21], v[40:41], off
	global_load_dwordx4 v[22:25], v[40:41], off offset:1024
	global_load_dwordx4 v[26:29], v[40:41], off offset:2048
	global_load_dwordx4 v[30:33], v[40:41], off offset:3072
	v_mbcnt_lo_u32_b32 v37, -1, 0
	v_mbcnt_hi_u32_b32 v37, -1, v37
	v_and_b32_e32 v40, 64, v37
	v_add_u32_e32 v40, 64, v40
	v_xor_b32_e32 v41, 32, v37
	v_cmp_lt_i32_e32 vcc, v41, v40
	s_load_dwordx4 s[16:19], s[0:1], 0xc0
	s_lshl_b32 s8, s80, 3
	s_cmpk_lg_i32 s80, 0x100
	s_cselect_b32 s8, s8, 0x100
	v_cndmask_b32_e32 v41, v37, v41, vcc
	v_lshlrev_b32_e32 v105, 2, v41
	v_xor_b32_e32 v41, 16, v37
	v_cmp_lt_i32_e32 vcc, v41, v40
	s_waitcnt lgkmcnt(0)
	s_add_u32 s0, s18, 0x4000
	s_addc_u32 s1, s19, 0
	v_cndmask_b32_e32 v41, v37, v41, vcc
	v_lshlrev_b32_e32 v138, 2, v41
	v_xor_b32_e32 v41, 8, v37
	v_cmp_lt_i32_e32 vcc, v41, v40
	s_add_u32 s12, s16, 0x4000
	v_readlane_b32 s18, v250, 2
	v_cndmask_b32_e32 v41, v37, v41, vcc
	v_lshlrev_b32_e32 v139, 2, v41
	v_xor_b32_e32 v41, 4, v37
	v_cmp_lt_i32_e32 vcc, v41, v40
	s_addc_u32 s13, s17, 0
	v_readlane_b32 s19, v250, 3
	v_cndmask_b32_e32 v41, v37, v41, vcc
	v_lshlrev_b32_e32 v140, 2, v41
	v_xor_b32_e32 v41, 2, v37
	v_cmp_lt_i32_e32 vcc, v41, v40
	v_lshlrev_b32_e32 v64, 2, v1
	v_mov_b32_e32 v1, 0x3800
	v_cndmask_b32_e32 v41, v37, v41, vcc
	v_lshlrev_b32_e32 v141, 2, v41
	v_xor_b32_e32 v41, 1, v37
	v_cmp_lt_i32_e32 vcc, v41, v40
	s_cmp_lg_u64 s[18:19], 0
	s_waitcnt vmcnt(0)
	v_lshl_or_b32 v70, v0, 5, v1
	v_lshlrev_b64 v[72:73], 14, v[34:35]
	v_and_b32_e32 v0, 63, v0
	v_cndmask_b32_e32 v37, v37, v41, vcc
	s_cselect_b64 s[10:11], -1, 0
	v_mov_b32_e32 v65, v36
	v_or_b32_e32 v46, 0x800, v64
	v_mov_b32_e32 v47, v36
	v_or_b32_e32 v50, 0x1000, v64
	v_mov_b32_e32 v51, v36
	v_or_b32_e32 v54, 0x1800, v64
	v_mov_b32_e32 v55, v36
	v_or_b32_e32 v58, 0x2000, v64
	v_mov_b32_e32 v59, v36
	v_or_b32_e32 v62, 0x2800, v64
	v_mov_b32_e32 v63, v36
	v_or_b32_e32 v66, 0x3000, v64
	v_mov_b32_e32 v67, v36
	v_mov_b32_e32 v71, v36
	v_lshl_or_b32 v72, v0, 5, v72
	s_ashr_i32 s9, s8, 31
	v_lshl_add_u64 v[38:39], s[4:5], 0, v[38:39]
	v_lshlrev_b32_e32 v142, 2, v37
	s_mov_b64 s[4:5], 0
	v_lshl_add_u64 v[40:41], s[12:13], 0, v[64:65]
	v_lshl_add_u64 v[42:43], s[0:1], 0, v[64:65]
	v_lshl_add_u64 v[44:45], s[12:13], 0, v[46:47]
	v_lshl_add_u64 v[46:47], s[0:1], 0, v[46:47]
	v_lshl_add_u64 v[48:49], s[12:13], 0, v[50:51]
	v_lshl_add_u64 v[50:51], s[0:1], 0, v[50:51]
	v_lshl_add_u64 v[52:53], s[12:13], 0, v[54:55]
	v_lshl_add_u64 v[54:55], s[0:1], 0, v[54:55]
	s_movk_i32 s16, 0x2000
	v_lshl_add_u64 v[56:57], s[12:13], 0, v[58:59]
	v_lshl_add_u64 v[58:59], s[0:1], 0, v[58:59]
	v_lshl_add_u64 v[60:61], s[12:13], 0, v[62:63]
	v_lshl_add_u64 v[62:63], s[0:1], 0, v[62:63]
	s_movk_i32 s17, 0x3000
	v_lshl_add_u64 v[64:65], s[12:13], 0, v[66:67]
	v_lshl_add_u64 v[66:67], s[0:1], 0, v[66:67]
	v_lshl_add_u64 v[68:69], s[12:13], 0, v[70:71]
	v_lshl_add_u64 v[70:71], s[0:1], 0, v[70:71]
	v_lshl_add_u64 v[0:1], s[18:19], 0, v[72:73]
	s_lshl_b64 s[12:13], s[8:9], 14
	s_add_i32 s9, s14, -1
	v_mov_b32_e32 v35, 0x3727c5ac
	s_mov_b32 s18, 0x800000
	s_branch .LBB0_2434
